# in-proj GEMM K-loop: last four vector address adds replaced by a scalar strided base so all 16 LDS-DMA loads use scalar-base addressing
# speedup vs baseline: 1.0046x; 1.0046x over previous
; #define PG8_STAGE(bufoff, gbase, voff) do { _Pragma("unroll") for (int _i = 0; _i < 2; ++_i) \
;         __builtin_amdgcn_global_load_lds((const unsigned*)((const char*)(gbase) + (voff)[_i]), (PG8_LAS unsigned*)(lds + (bufoff) + ldsw + _i * 8192), 16, 0, 0); } while (0)
; #define PG8_LDA(dst, b, h) do { _Pragma("unroll") for (int m = 0; m < 4; ++m) _Pragma("unroll") for (int k = 0; k < 2; ++k) dst[m][k] = *(const PG8_LAS bf16x8*)(lds + PG8_SA(b, h) + aoff + m * 2048 + k * 1024); } while (0)
; #define PG8_LDB(dst, b, h) do { _Pragma("unroll") for (int n = 0; n < 2; ++n) _Pragma("unroll") for (int k = 0; k < 2; ++k) dst[n][k] = *(const PG8_LAS bf16x8*)(lds + PG8_SB(b, h) + boff + n * 2048 + k * 1024); } while (0)
; #define PG8_MMA(ai, bj, At, Bt) do { __builtin_amdgcn_s_setprio(1); _Pragma("unroll") for (int m = 0; m < 4; ++m) _Pragma("unroll") for (int n = 0; n < 2; ++n) _Pragma("unroll") for (int k = 0; k < 2; ++k) \
;         acc[ai][bj][m][n] = __builtin_amdgcn_mfma_f32_16x16x32_bf16(Bt[n][k], At[m][k], acc[ai][bj][m][n], 0, 0, 0); __builtin_amdgcn_s_setprio(0); } while (0)
; #define PG8_WAIT_V(n) asm volatile("s_waitcnt vmcnt(" #n ")" ::: "memory")
; #define PG8_WAIT_L(n) asm volatile("s_waitcnt lgkmcnt(" #n ")" ::: "memory")
; template <class Epi, class Sched, bool ALIGN_EPI = false, bool SP2 = false>
; __device__ __forceinline__ void gemm_phase(PG8_LAS unsigned char* lds, const Gemm g, const Sched& S, const Epi& E) {
;     ...
;             const bool last = (t == nt - 2);
;             const char* a1 = cA + (size_t)(t + 1) * kstep;
;             const char* a2 = last ? nA : cA + (size_t)(t + 2) * kstep; const char* b2 = last ? nB : cB + (size_t)(t + 2) * kstep;
;             const char* a3 = a2 + kstep; const char* b3 = b2 + kstep;
;             if (last && has_next) S.a_ready(nxt);
;             if constexpr (SP2) {
;             PG8_LDB(B0, 0, 0); PG8_LDB(B1, 0, 1); PG8_SCHED; PG8_LDA(At, 0, 0); PG8_STAGE(PG8_SA(1, 1), a1 + hstep, voffA);
;             PG8_WAIT_V(8); PG8_WAIT_L(0); PG8_BAR; PG8_MMA(0, 0, At, B0); PG8_MMA(0, 1, At, B1); PG8_BAR; PG8_SCHED;
;             PG8_LDA(At, 0, 1); PG8_STAGE(PG8_SB(0, 0), b2, voffB); PG8_STAGE(PG8_SB(0, 1), b2 + hstep, voffB); PG8_STAGE(PG8_SA(0, 0), a2, voffA);
;             PG8_WAIT_V(8); PG8_WAIT_L(0); PG8_BAR; PG8_MMA(1, 0, At, B0); PG8_MMA(1, 1, At, B1); PG8_BAR; PG8_SCHED;
.LBB0_123:
	s_add_u32 s8, s6, 0xfff80080
	s_addc_u32 s9, s7, -1
	s_add_i32 s43, 0, 0x10000
	s_cmp_eq_u32 s42, 28
	s_cselect_b32 s23, s15, s9
	s_cselect_b32 s22, s24, s8
	s_cselect_b32 s9, s17, s41
	s_cselect_b32 s8, s25, s40
	s_add_i32 s48, 0, 0x14000
	v_add_u32_e32 v172, s43, v165
	v_add_u32_e32 v188, s48, v165
	ds_read_b128 v[156:159], v172
	ds_read_b128 v[160:163], v172 offset:1024
	ds_read_b128 v[168:171], v172 offset:2048
	ds_read_b128 v[172:175], v172 offset:3072
	ds_read_b128 v[176:179], v188
	ds_read_b128 v[180:183], v188 offset:1024
	ds_read_b128 v[184:187], v188 offset:2048
	ds_read_b128 v[188:191], v188 offset:3072
	s_add_i32 m0, s31, 0xc000
	ds_read_b128 v[192:195], v167
	ds_read_b128 v[196:199], v167 offset:1024
	ds_read_b128 v[200:203], v167 offset:2048
	ds_read_b128 v[204:207], v167 offset:3072
	ds_read_b128 v[208:211], v167 offset:4096
	ds_read_b128 v[212:215], v167 offset:5120
	ds_read_b128 v[216:219], v167 offset:6144
	ds_read_b128 v[224:227], v167 offset:7168
	global_load_lds_dwordx4 v152, s[6:7]
	s_add_i32 m0, s31, 0xe000
	s_nop 0
	global_load_lds_dwordx4 v154, s[6:7]
	s_waitcnt vmcnt(8) lgkmcnt(0)
	s_barrier
	v_mfma_f32_16x16x32_bf16 v[144:147], v[156:159], v[192:195], v[144:147]
	v_mfma_f32_16x16x32_bf16 v[122:125], v[168:171], v[192:195], v[122:125]
	v_mfma_f32_16x16x32_bf16 v[110:113], v[156:159], v[200:203], v[110:113]
	v_mfma_f32_16x16x32_bf16 v[106:109], v[168:171], v[200:203], v[106:109]
	v_mfma_f32_16x16x32_bf16 v[94:97], v[156:159], v[208:211], v[94:97]
	v_mfma_f32_16x16x32_bf16 v[90:93], v[168:171], v[208:211], v[90:93]
	v_mfma_f32_16x16x32_bf16 v[78:81], v[156:159], v[216:219], v[78:81]
	v_mfma_f32_16x16x32_bf16 v[74:77], v[168:171], v[216:219], v[74:77]
	v_mfma_f32_16x16x32_bf16 v[144:147], v[160:163], v[196:199], v[144:147]
	v_mfma_f32_16x16x32_bf16 v[122:125], v[172:175], v[196:199], v[122:125]
	v_mfma_f32_16x16x32_bf16 v[110:113], v[160:163], v[204:207], v[110:113]
	v_mfma_f32_16x16x32_bf16 v[106:109], v[172:175], v[204:207], v[106:109]
	v_mfma_f32_16x16x32_bf16 v[94:97], v[160:163], v[212:215], v[94:97]
	v_mfma_f32_16x16x32_bf16 v[90:93], v[172:175], v[212:215], v[90:93]
	v_mfma_f32_16x16x32_bf16 v[78:81], v[160:163], v[224:227], v[78:81]
	v_mfma_f32_16x16x32_bf16 v[74:77], v[172:175], v[224:227], v[74:77]
	v_mfma_f32_16x16x32_bf16 v[118:121], v[176:179], v[192:195], v[118:121]
	v_mfma_f32_16x16x32_bf16 v[114:117], v[184:187], v[192:195], v[114:117]
	v_mfma_f32_16x16x32_bf16 v[102:105], v[176:179], v[200:203], v[102:105]
	v_mfma_f32_16x16x32_bf16 v[98:101], v[184:187], v[200:203], v[98:101]
	v_mfma_f32_16x16x32_bf16 v[86:89], v[176:179], v[208:211], v[86:89]
	v_mfma_f32_16x16x32_bf16 v[82:85], v[184:187], v[208:211], v[82:85]
	v_mfma_f32_16x16x32_bf16 v[70:73], v[176:179], v[216:219], v[70:73]
	v_mfma_f32_16x16x32_bf16 v[66:69], v[184:187], v[216:219], v[66:69]
	v_mfma_f32_16x16x32_bf16 v[118:121], v[180:183], v[196:199], v[118:121]
	v_mfma_f32_16x16x32_bf16 v[114:117], v[188:191], v[196:199], v[114:117]
	v_mfma_f32_16x16x32_bf16 v[102:105], v[180:183], v[204:207], v[102:105]
	v_mfma_f32_16x16x32_bf16 v[98:101], v[188:191], v[204:207], v[98:101]
	v_mfma_f32_16x16x32_bf16 v[86:89], v[180:183], v[212:215], v[86:89]
	v_mfma_f32_16x16x32_bf16 v[82:85], v[188:191], v[212:215], v[82:85]
	v_mfma_f32_16x16x32_bf16 v[70:73], v[180:183], v[224:227], v[70:73]
	v_mfma_f32_16x16x32_bf16 v[66:69], v[188:191], v[224:227], v[66:69]
	s_barrier
	s_add_i32 s43, s43, s30
	s_mov_b32 m0, s43
	ds_read_b128 v[192:195], v167 offset:16384
	ds_read_b128 v[196:199], v167 offset:17408
	ds_read_b128 v[200:203], v167 offset:18432
	ds_read_b128 v[204:207], v167 offset:19456
	ds_read_b128 v[208:211], v167 offset:20480
	ds_read_b128 v[212:215], v167 offset:21504
	ds_read_b128 v[216:219], v167 offset:22528
	ds_read_b128 v[224:227], v167 offset:23552
	global_load_lds_dwordx4 v0, s[8:9]
	s_add_i32 m0, s43, 0x2000
	s_add_u32 s82, s8, 0x80000
	s_addc_u32 s83, s9, 0
	s_add_i32 s43, s48, s30
	global_load_lds_dwordx4 v126, s[8:9]
	s_mov_b32 m0, s43
	s_nop 0
	global_load_lds_dwordx4 v0, s[82:83]
	s_add_i32 m0, s43, 0x2000
	s_nop 0
	global_load_lds_dwordx4 v126, s[82:83]
	s_mov_b32 m0, s31
	s_nop 0
	global_load_lds_dwordx4 v150, s[22:23]
	s_mov_b32 m0, s34
	s_nop 0
	global_load_lds_dwordx4 v148, s[22:23]
	s_waitcnt vmcnt(8) lgkmcnt(0)
	s_barrier
	v_mfma_f32_16x16x32_bf16 v[62:65], v[156:159], v[192:195], v[62:65]
	v_mfma_f32_16x16x32_bf16 v[58:61], v[168:171], v[192:195], v[58:61]
	v_mfma_f32_16x16x32_bf16 v[46:49], v[156:159], v[200:203], v[46:49]
	v_mfma_f32_16x16x32_bf16 v[42:45], v[168:171], v[200:203], v[42:45]
	v_mfma_f32_16x16x32_bf16 v[30:33], v[156:159], v[208:211], v[30:33]
	v_mfma_f32_16x16x32_bf16 v[26:29], v[168:171], v[208:211], v[26:29]
	v_mfma_f32_16x16x32_bf16 v[14:17], v[156:159], v[216:219], v[14:17]
	v_mfma_f32_16x16x32_bf16 v[10:13], v[168:171], v[216:219], v[10:13]
	v_mfma_f32_16x16x32_bf16 v[62:65], v[160:163], v[196:199], v[62:65]
	v_mfma_f32_16x16x32_bf16 v[58:61], v[172:175], v[196:199], v[58:61]
	v_mfma_f32_16x16x32_bf16 v[46:49], v[160:163], v[204:207], v[46:49]
	v_mfma_f32_16x16x32_bf16 v[42:45], v[172:175], v[204:207], v[42:45]
	v_mfma_f32_16x16x32_bf16 v[30:33], v[160:163], v[212:215], v[30:33]
	v_mfma_f32_16x16x32_bf16 v[26:29], v[172:175], v[212:215], v[26:29]
	v_mfma_f32_16x16x32_bf16 v[14:17], v[160:163], v[224:227], v[14:17]
	v_mfma_f32_16x16x32_bf16 v[10:13], v[172:175], v[224:227], v[10:13]
	v_mfma_f32_16x16x32_bf16 v[54:57], v[176:179], v[192:195], v[54:57]
	v_mfma_f32_16x16x32_bf16 v[50:53], v[184:187], v[192:195], v[50:53]
	v_mfma_f32_16x16x32_bf16 v[38:41], v[176:179], v[200:203], v[38:41]
	v_mfma_f32_16x16x32_bf16 v[34:37], v[184:187], v[200:203], v[34:37]
	v_mfma_f32_16x16x32_bf16 v[22:25], v[176:179], v[208:211], v[22:25]
	v_mfma_f32_16x16x32_bf16 v[18:21], v[184:187], v[208:211], v[18:21]
	v_mfma_f32_16x16x32_bf16 v[6:9], v[176:179], v[216:219], v[6:9]
	v_mfma_f32_16x16x32_bf16 v[2:5], v[184:187], v[216:219], v[2:5]
	v_mfma_f32_16x16x32_bf16 v[54:57], v[180:183], v[196:199], v[54:57]
	v_mfma_f32_16x16x32_bf16 v[50:53], v[188:191], v[196:199], v[50:53]
	v_mfma_f32_16x16x32_bf16 v[38:41], v[180:183], v[204:207], v[38:41]
	v_mfma_f32_16x16x32_bf16 v[34:37], v[188:191], v[204:207], v[34:37]
	v_mfma_f32_16x16x32_bf16 v[22:25], v[180:183], v[212:215], v[22:25]
	v_mfma_f32_16x16x32_bf16 v[18:21], v[188:191], v[212:215], v[18:21]
	v_mfma_f32_16x16x32_bf16 v[6:9], v[180:183], v[224:227], v[6:9]
	v_mfma_f32_16x16x32_bf16 v[2:5], v[188:191], v[224:227], v[2:5]
	s_barrier
; #define PG8_STAGE(bufoff, gbase, voff) do { _Pragma("unroll") for (int _i = 0; _i < 2; ++_i) \
;         __builtin_amdgcn_global_load_lds((const unsigned*)((const char*)(gbase) + (voff)[_i]), (PG8_LAS unsigned*)(lds + (bufoff) + ldsw + _i * 8192), 16, 0, 0); } while (0)
; #define PG8_LDA(dst, b, h) do { _Pragma("unroll") for (int m = 0; m < 4; ++m) _Pragma("unroll") for (int k = 0; k < 2; ++k) dst[m][k] = *(const PG8_LAS bf16x8*)(lds + PG8_SA(b, h) + aoff + m * 2048 + k * 1024); } while (0)
; #define PG8_LDB(dst, b, h) do { _Pragma("unroll") for (int n = 0; n < 2; ++n) _Pragma("unroll") for (int k = 0; k < 2; ++k) dst[n][k] = *(const PG8_LAS bf16x8*)(lds + PG8_SB(b, h) + boff + n * 2048 + k * 1024); } while (0)
; #define PG8_MMA(ai, bj, At, Bt) do { __builtin_amdgcn_s_setprio(1); _Pragma("unroll") for (int m = 0; m < 4; ++m) _Pragma("unroll") for (int n = 0; n < 2; ++n) _Pragma("unroll") for (int k = 0; k < 2; ++k) \
;         acc[ai][bj][m][n] = __builtin_amdgcn_mfma_f32_16x16x32_bf16(Bt[n][k], At[m][k], acc[ai][bj][m][n], 0, 0, 0); __builtin_amdgcn_s_setprio(0); } while (0)
; #define PG8_WAIT_V(n) asm volatile("s_waitcnt vmcnt(" #n ")" ::: "memory")
; #define PG8_WAIT_L(n) asm volatile("s_waitcnt lgkmcnt(" #n ")" ::: "memory")
; #define PG8_BAR __builtin_amdgcn_s_barrier()
; #define PG8_SCHED __builtin_amdgcn_sched_barrier(0)
; template <class Epi, class Sched, bool ALIGN_EPI = false, bool SP2 = false>
; __device__ __forceinline__ void gemm_phase(PG8_LAS unsigned char* lds, const Gemm g, const Sched& S, const Epi& E) {
;     ...
;             PG8_LDB(B0, 1, 0); PG8_LDB(B1, 1, 1); PG8_SCHED; PG8_LDA(At, 1, 0); PG8_STAGE(PG8_SA(0, 1), a2 + hstep, voffA);
;             PG8_WAIT_V(8); PG8_WAIT_L(0); PG8_BAR; PG8_MMA(0, 0, At, B0); PG8_MMA(0, 1, At, B1); PG8_BAR; PG8_SCHED;
;             PG8_LDA(At, 1, 1); PG8_STAGE(PG8_SB(1, 0), b3, voffB); PG8_STAGE(PG8_SB(1, 1), b3 + hstep, voffB); PG8_STAGE(PG8_SA(1, 0), a3, voffA);
;             PG8_WAIT_V(8); PG8_WAIT_L(0); PG8_BAR; PG8_MMA(1, 0, At, B0); PG8_MMA(1, 1, At, B1); PG8_BAR; PG8_SCHED;
	s_add_i32 s43, 0, 0x18000
	s_add_i32 s48, 0, 0x1c000
	v_add_u32_e32 v172, s43, v165
	v_add_u32_e32 v188, s48, v165
	ds_read_b128 v[156:159], v172
	ds_read_b128 v[160:163], v172 offset:1024
	ds_read_b128 v[168:171], v172 offset:2048
	ds_read_b128 v[172:175], v172 offset:3072
	ds_read_b128 v[176:179], v188
	ds_read_b128 v[180:183], v188 offset:1024
	ds_read_b128 v[184:187], v188 offset:2048
	ds_read_b128 v[188:191], v188 offset:3072
	s_add_u32 s22, s22, 0x80000
	s_addc_u32 s23, s23, 0
	s_mov_b32 m0, s35
	ds_read_b128 v[192:195], v167 offset:32768
	ds_read_b128 v[196:199], v167 offset:33792
	ds_read_b128 v[200:203], v167 offset:34816
	ds_read_b128 v[204:207], v167 offset:35840
	ds_read_b128 v[208:211], v167 offset:36864
	ds_read_b128 v[212:215], v167 offset:37888
	ds_read_b128 v[216:219], v167 offset:38912
	ds_read_b128 v[224:227], v167 offset:39936
	global_load_lds_dwordx4 v150, s[22:23]
	s_mov_b32 m0, s36
	s_nop 0
	global_load_lds_dwordx4 v148, s[22:23]
	s_waitcnt vmcnt(8) lgkmcnt(0)
	s_barrier
	v_mfma_f32_16x16x32_bf16 v[144:147], v[156:159], v[192:195], v[144:147]
	v_mfma_f32_16x16x32_bf16 v[122:125], v[168:171], v[192:195], v[122:125]
	v_mfma_f32_16x16x32_bf16 v[110:113], v[156:159], v[200:203], v[110:113]
	v_mfma_f32_16x16x32_bf16 v[106:109], v[168:171], v[200:203], v[106:109]
	v_mfma_f32_16x16x32_bf16 v[94:97], v[156:159], v[208:211], v[94:97]
	v_mfma_f32_16x16x32_bf16 v[90:93], v[168:171], v[208:211], v[90:93]
	v_mfma_f32_16x16x32_bf16 v[78:81], v[156:159], v[216:219], v[78:81]
	v_mfma_f32_16x16x32_bf16 v[74:77], v[168:171], v[216:219], v[74:77]
	v_mfma_f32_16x16x32_bf16 v[144:147], v[160:163], v[196:199], v[144:147]
	v_mfma_f32_16x16x32_bf16 v[122:125], v[172:175], v[196:199], v[122:125]
	v_mfma_f32_16x16x32_bf16 v[110:113], v[160:163], v[204:207], v[110:113]
	v_mfma_f32_16x16x32_bf16 v[106:109], v[172:175], v[204:207], v[106:109]
	v_mfma_f32_16x16x32_bf16 v[94:97], v[160:163], v[212:215], v[94:97]
	v_mfma_f32_16x16x32_bf16 v[90:93], v[172:175], v[212:215], v[90:93]
	v_mfma_f32_16x16x32_bf16 v[78:81], v[160:163], v[224:227], v[78:81]
	v_mfma_f32_16x16x32_bf16 v[74:77], v[172:175], v[224:227], v[74:77]
	v_mfma_f32_16x16x32_bf16 v[118:121], v[176:179], v[192:195], v[118:121]
	v_mfma_f32_16x16x32_bf16 v[114:117], v[184:187], v[192:195], v[114:117]
	v_mfma_f32_16x16x32_bf16 v[102:105], v[176:179], v[200:203], v[102:105]
	v_mfma_f32_16x16x32_bf16 v[98:101], v[184:187], v[200:203], v[98:101]
	v_mfma_f32_16x16x32_bf16 v[86:89], v[176:179], v[208:211], v[86:89]
	v_mfma_f32_16x16x32_bf16 v[82:85], v[184:187], v[208:211], v[82:85]
	v_mfma_f32_16x16x32_bf16 v[70:73], v[176:179], v[216:219], v[70:73]
	v_mfma_f32_16x16x32_bf16 v[66:69], v[184:187], v[216:219], v[66:69]
	v_mfma_f32_16x16x32_bf16 v[118:121], v[180:183], v[196:199], v[118:121]
	v_mfma_f32_16x16x32_bf16 v[114:117], v[188:191], v[196:199], v[114:117]
	v_mfma_f32_16x16x32_bf16 v[102:105], v[180:183], v[204:207], v[102:105]
	v_mfma_f32_16x16x32_bf16 v[98:101], v[188:191], v[204:207], v[98:101]
	v_mfma_f32_16x16x32_bf16 v[86:89], v[180:183], v[212:215], v[86:89]
	v_mfma_f32_16x16x32_bf16 v[82:85], v[188:191], v[212:215], v[82:85]
	v_mfma_f32_16x16x32_bf16 v[70:73], v[180:183], v[224:227], v[70:73]
	v_mfma_f32_16x16x32_bf16 v[66:69], v[188:191], v[224:227], v[66:69]
	s_barrier
	s_add_u32 s82, s22, s64
	s_addc_u32 s83, s23, s65
	s_add_u32 s82, s82, 0xfff80000
	s_addc_u32 s83, s83, -1
	s_mov_b32 m0, s37
	s_add_i32 s22, s43, s30
	global_load_lds_dwordx4 v150, s[82:83]
	s_mov_b32 m0, s76
	s_nop 0
	global_load_lds_dwordx4 v148, s[82:83]
	s_add_u32 s82, s8, s64
	s_addc_u32 s83, s9, s65
	s_mov_b32 m0, s22
	ds_read_b128 v[192:195], v167 offset:49152
	ds_read_b128 v[196:199], v167 offset:50176
	ds_read_b128 v[200:203], v167 offset:51200
	ds_read_b128 v[204:207], v167 offset:52224
	ds_read_b128 v[208:211], v167 offset:53248
	ds_read_b128 v[212:215], v167 offset:54272
	ds_read_b128 v[216:219], v167 offset:55296
	ds_read_b128 v[224:227], v167 offset:56320
	global_load_lds_dwordx4 v0, s[82:83]
	s_add_i32 m0, s22, 0x2000
	s_add_u32 s8, s8, 0x80080
	s_addc_u32 s9, s9, 0
	s_add_i32 s22, s48, s30
	global_load_lds_dwordx4 v126, s[82:83]
	s_mov_b32 m0, s22
	s_nop 0
	global_load_lds_dwordx4 v0, s[8:9]
	s_add_i32 m0, s22, 0x2000
	s_nop 0
	global_load_lds_dwordx4 v126, s[8:9]
	s_waitcnt vmcnt(8) lgkmcnt(0)
	s_barrier
	v_mfma_f32_16x16x32_bf16 v[62:65], v[156:159], v[192:195], v[62:65]
	v_mfma_f32_16x16x32_bf16 v[58:61], v[168:171], v[192:195], v[58:61]
	v_mfma_f32_16x16x32_bf16 v[46:49], v[156:159], v[200:203], v[46:49]
	v_mfma_f32_16x16x32_bf16 v[42:45], v[168:171], v[200:203], v[42:45]
	v_mfma_f32_16x16x32_bf16 v[30:33], v[156:159], v[208:211], v[30:33]
	v_mfma_f32_16x16x32_bf16 v[26:29], v[168:171], v[208:211], v[26:29]
	v_mfma_f32_16x16x32_bf16 v[14:17], v[156:159], v[216:219], v[14:17]
	v_mfma_f32_16x16x32_bf16 v[10:13], v[168:171], v[216:219], v[10:13]
	v_mfma_f32_16x16x32_bf16 v[62:65], v[160:163], v[196:199], v[62:65]
	v_mfma_f32_16x16x32_bf16 v[58:61], v[172:175], v[196:199], v[58:61]
	v_mfma_f32_16x16x32_bf16 v[46:49], v[160:163], v[204:207], v[46:49]
	v_mfma_f32_16x16x32_bf16 v[42:45], v[172:175], v[204:207], v[42:45]
	v_mfma_f32_16x16x32_bf16 v[30:33], v[160:163], v[212:215], v[30:33]
	v_mfma_f32_16x16x32_bf16 v[26:29], v[172:175], v[212:215], v[26:29]
	v_mfma_f32_16x16x32_bf16 v[14:17], v[160:163], v[224:227], v[14:17]
	v_mfma_f32_16x16x32_bf16 v[10:13], v[172:175], v[224:227], v[10:13]
	v_mfma_f32_16x16x32_bf16 v[54:57], v[176:179], v[192:195], v[54:57]
	v_mfma_f32_16x16x32_bf16 v[50:53], v[184:187], v[192:195], v[50:53]
	v_mfma_f32_16x16x32_bf16 v[38:41], v[176:179], v[200:203], v[38:41]
	v_mfma_f32_16x16x32_bf16 v[34:37], v[184:187], v[200:203], v[34:37]
	v_mfma_f32_16x16x32_bf16 v[22:25], v[176:179], v[208:211], v[22:25]
	v_mfma_f32_16x16x32_bf16 v[18:21], v[184:187], v[208:211], v[18:21]
	v_mfma_f32_16x16x32_bf16 v[6:9], v[176:179], v[216:219], v[6:9]
	v_mfma_f32_16x16x32_bf16 v[2:5], v[184:187], v[216:219], v[2:5]
	v_mfma_f32_16x16x32_bf16 v[54:57], v[180:183], v[196:199], v[54:57]
	v_mfma_f32_16x16x32_bf16 v[50:53], v[188:191], v[196:199], v[50:53]
	v_mfma_f32_16x16x32_bf16 v[38:41], v[180:183], v[204:207], v[38:41]
	v_mfma_f32_16x16x32_bf16 v[34:37], v[188:191], v[204:207], v[34:37]
	v_mfma_f32_16x16x32_bf16 v[22:25], v[180:183], v[212:215], v[22:25]
	v_mfma_f32_16x16x32_bf16 v[18:21], v[188:191], v[212:215], v[18:21]
	v_mfma_f32_16x16x32_bf16 v[6:9], v[180:183], v[224:227], v[6:9]
	v_mfma_f32_16x16x32_bf16 v[2:5], v[188:191], v[224:227], v[2:5]
	s_barrier
	s_add_i32 s42, s42, 2
	s_add_u32 s6, s6, 0x100
	s_addc_u32 s7, s7, 0
	s_add_u32 s40, s40, 0x100
	s_addc_u32 s41, s41, 0
	s_cmp_gt_u32 s42, 29
	s_cbranch_scc0 .LBB0_123
	s_and_b64 vcc, exec, s[12:13]
	s_cbranch_vccz .LBB0_126
	s_barrier
